# rwkv_prep_item: L2 warm-up of the token-shift U/MISC rows by one dword load per thread at item entry (on top of slab+rwkv loader+ssd batch+p0wait)
# baseline (speedup 1.0000x reference)
; __device__ __forceinline__ int rwkv_tok(int b, int j) { if (j < LCTX) return TLAT + b * LCTX + j; const int s = j - LCTX; return b * LSEQ + (s & 31) * 64 + (s >> 5); }
; __device__ __forceinline__ void rwkv_prep_item(KArgs a, int l, int item, LAS unsigned char* lds, int tid, int lane, int wave) {
;     ...
;     { const bf16* WLT = (const bf16*)(ws + OFF_WLT) + (size_t)l * 512 * 320 + (size_t)(64 * wave + (lane & 15)) * 320 + (lane >> 4) * 8;
; #pragma unroll
;       for (int ks = 0; ks < 10; ++ks)
; #pragma unroll
;           for (int nt = 0; nt < 4; ++nt) wfr[ks][nt] = *(const bf16x8*)(WLT + (size_t)nt * 16 * 320 + ks * 32); }
; #pragma unroll
;     for (int it_ = 0; it_ < 6; ++it_) { const int idx = tid + it_ * NTHR; const int i = idx / 192, c8 = idx % 192, jj = j0 + i;
;         const bool hp = isctx ? (jj - 1 >= 0) : (jj - 1 >= LCTX), hn = isctx ? (jj + 1 < LCTX) : (jj + 1 < RJ);
;         const v4u c = *(const v4u*)(U + (size_t)rwkv_tok(b, jj) * NU + URKV + c8 * 8);
;         v4u p = (v4u){0u, 0u, 0u, 0u}, n = p;
;         if (hp) p = *(const v4u*)(U + (size_t)rwkv_tok(b, jj - 1) * NU + URKV + c8 * 8);
;         if (hn) n = *(const v4u*)(U + (size_t)rwkv_tok(b, jj + 1) * NU + URKV + c8 * 8);
.LBB0_612:
	v_readlane_b32 s0, v254, 37
	v_and_b32_e32 v0, 15, v182
	v_readlane_b32 s1, v254, 38
	v_ashrrev_i32_e32 v184, 4, v182
	v_or_b32_e32 v174, s19, v0
	v_mov_b64_e32 v[2:3], s[0:1]
	s_movk_i32 s0, 0x280
	v_lshlrev_b32_e32 v176, 3, v184
	v_mad_i64_i32 v[2:3], s[0:1], v174, s0, v[2:3]
	v_ashrrev_i32_e32 v177, 31, v176
	v_lshl_add_u64 v[2:3], v[176:177], 1, v[2:3]
	s_movk_i32 s0, 0x2000
	v_add_co_u32_e32 v4, vcc, s0, v2
	s_movk_i32 s0, 0x5000
	s_nop 0
	v_addc_co_u32_e32 v5, vcc, 0, v3, vcc
	v_add_co_u32_e32 v6, vcc, s0, v2
	s_movk_i32 s0, 0x7000
	s_nop 0
	v_addc_co_u32_e32 v7, vcc, 0, v3, vcc
	v_add_co_u32_e32 v162, vcc, s0, v2
	s_mul_hi_i32 s0, s9, 0x38e38e39
	s_nop 0
	v_addc_co_u32_e32 v163, vcc, 0, v3, vcc
	global_load_dwordx4 v[146:149], v[2:3], off
	global_load_dwordx4 v[142:145], v[2:3], off offset:64
	global_load_dwordx4 v[150:153], v[4:5], off offset:2048
	global_load_dwordx4 v[138:141], v[4:5], off offset:2112
	global_load_dwordx4 v[154:157], v[6:7], off
	global_load_dwordx4 v[134:137], v[6:7], off offset:64
	global_load_dwordx4 v[158:161], v[162:163], off offset:2048
	global_load_dwordx4 v[130:133], v[162:163], off offset:2112
	global_load_dwordx4 v[118:121], v[2:3], off offset:128
	global_load_dwordx4 v[110:113], v[2:3], off offset:192
	global_load_dwordx4 v[126:129], v[4:5], off offset:2176
	global_load_dwordx4 v[106:109], v[4:5], off offset:2240
	global_load_dwordx4 v[122:125], v[6:7], off offset:128
	global_load_dwordx4 v[102:105], v[6:7], off offset:192
	global_load_dwordx4 v[114:117], v[162:163], off offset:2176
	global_load_dwordx4 v[98:101], v[162:163], off offset:2240
	global_load_dwordx4 v[94:97], v[2:3], off offset:256
	global_load_dwordx4 v[78:81], v[2:3], off offset:320
	global_load_dwordx4 v[90:93], v[4:5], off offset:2304
	global_load_dwordx4 v[74:77], v[4:5], off offset:2368
	global_load_dwordx4 v[86:89], v[6:7], off offset:256
	global_load_dwordx4 v[70:73], v[6:7], off offset:320
	global_load_dwordx4 v[82:85], v[162:163], off offset:2304
	global_load_dwordx4 v[66:69], v[162:163], off offset:2368
	global_load_dwordx4 v[62:65], v[2:3], off offset:384
	global_load_dwordx4 v[46:49], v[2:3], off offset:448
	global_load_dwordx4 v[58:61], v[4:5], off offset:2432
	global_load_dwordx4 v[42:45], v[4:5], off offset:2496
	global_load_dwordx4 v[54:57], v[6:7], off offset:384
	global_load_dwordx4 v[38:41], v[6:7], off offset:448
	global_load_dwordx4 v[50:53], v[162:163], off offset:2432
	global_load_dwordx4 v[34:37], v[162:163], off offset:2496
	global_load_dwordx4 v[30:33], v[2:3], off offset:512
	global_load_dwordx4 v[14:17], v[2:3], off offset:576
	global_load_dwordx4 v[26:29], v[4:5], off offset:2560
	global_load_dwordx4 v[10:13], v[4:5], off offset:2624
	global_load_dwordx4 v[22:25], v[6:7], off offset:512
	s_nop 0
	global_load_dwordx4 v[6:9], v[6:7], off offset:576
	s_nop 0
	global_load_dwordx4 v[18:21], v[162:163], off offset:2560
	global_load_dwordx4 v[2:5], v[162:163], off offset:2624
	s_lshr_b32 s1, s0, 31
	s_ashr_i32 s8, s0, 5
	s_add_i32 s8, s8, s1
	s_mul_i32 s0, s8, 0x90
	v_mul_hi_i32 v162, v183, s18
	s_sub_i32 s7, s9, s0
	v_lshrrev_b32_e32 v163, 31, v162
	v_ashrrev_i32_e32 v162, 5, v162
	s_lshl_b32 s6, s7, 4
	v_add_u32_e32 v185, v162, v163
	v_add_u32_e32 v186, s6, v185
	s_movk_i32 s3, 0x8ff
	s_cmpk_lt_i32 s6, 0x100
	s_cselect_b32 s2, 0, 0x100
	s_cselect_b32 s3, 0xff, s3
	s_lshl_b32 s4, s8, 8
	s_addk_i32 s4, 0x2000
	s_lshl_b32 s5, s8, 11
	v_mul_u32_u24_e32 v164, 0xaaab, v183
	v_lshrrev_b32_e32 v164, 20, v164
	v_mul_u32_u24_e32 v165, 24, v164
	v_sub_u32_e32 v165, v183, v165
	v_add3_u32 v166, v164, s6, -1
	v_max_i32_e32 v166, s2, v166
	v_min_i32_e32 v166, s3, v166
	v_add_u32_e32 v167, 0xffffff00, v166
	v_lshlrev_b32_e32 v168, 6, v166
	v_and_b32_e32 v168, 0x7c0, v168
	v_lshrrev_b32_e32 v167, 5, v167
	v_add3_u32 v167, v167, s5, v168
	v_add_u32_e32 v168, s4, v166
	v_cmp_gt_i32_e32 vcc, 0x100, v166
	v_readlane_b32 s0, v254, 39
	v_readlane_b32 s1, v254, 40
	v_cndmask_b32_e32 v167, v167, v168, vcc
	v_lshlrev_b32_e32 v164, 7, v165
	v_mov_b64_e32 v[168:169], s[0:1]
	s_movk_i32 s0, 0x6c00
	v_mad_i64_i32 v[170:171], s[0:1], v167, s0, v[168:169]
	v_add_u32_e32 v164, 0x1000, v164
	s_nop 0
	v_add_co_u32_e32 v170, vcc, v170, v164
	s_nop 1
	v_addc_co_u32_e32 v171, vcc, 0, v171, vcc
	v_cmp_gt_u32_e32 vcc, 0x1b0, v183
	s_and_saveexec_b64 s[0:1], vcc
	global_load_dword v196, v[170:171], off offset:1024
	v_cmp_gt_u32_e32 vcc, 10, v165
	v_lshlrev_b32_e32 v167, 11, v167
	v_mov_b32_e32 v169, 0
	v_lshl_add_u32 v168, v165, 7, v167
	s_and_b64 exec, exec, vcc
	v_lshl_add_u64 v[170:171], s[38:39], 0, v[168:169]
	global_load_dword v197, v[170:171], off offset:256
	s_mov_b64 exec, s[0:1]
	s_movk_i32 s0, 0xff
	s_lshl_b32 s9, s8, 11
	v_cmp_lt_i32_e32 vcc, s0, v186
	s_and_saveexec_b64 s[0:1], vcc
	s_xor_b64 s[0:1], exec, s[0:1]
	v_lshlrev_b32_e32 v163, 6, v186
	v_add_u32_e32 v162, 0xffffff00, v186
	v_and_b32_e32 v163, 0x7c0, v163
	v_or_b32_e32 v163, s9, v163
	v_lshrrev_b32_e32 v162, 5, v162
	v_add_u32_e32 v162, v163, v162
	s_or_saveexec_b64 s[2:3], s[0:1]
	s_load_dwordx2 s[0:1], s[36:37], 0xa8
	s_lshl_b32 s10, s8, 8
	s_addk_i32 s10, 0x2000
	s_xor_b64 exec, exec, s[2:3]
	v_add_u32_e32 v162, s10, v186
	s_or_b64 exec, exec, s[2:3]
	v_mul_lo_u32 v163, v185, s97
	v_readlane_b32 s2, v254, 39
	v_sub_u32_e32 v177, v183, v163
	v_readlane_b32 s3, v254, 40
	v_lshlrev_b32_e32 v178, 3, v177
	v_ashrrev_i32_e32 v179, 31, v178
	v_mov_b64_e32 v[164:165], s[2:3]
	s_movk_i32 s2, 0x6c00
	v_mad_i64_i32 v[162:163], s[2:3], v162, s2, v[164:165]
	v_lshl_add_u64 v[162:163], v[178:179], 1, v[162:163]
	v_add_co_u32_e32 v162, vcc, 0x1000, v162
	s_cmp_lt_i32 s7, 16
	s_nop 0
	v_addc_co_u32_e32 v163, vcc, 0, v163, vcc
	global_load_dwordx4 v[162:165], v[162:163], off offset:1024
	s_cselect_b64 s[40:41], -1, 0
	s_and_b64 s[2:3], s[40:41], exec
	s_cselect_b32 s11, 0, 0x100
	v_cmp_lt_i32_e32 vcc, s11, v186
	v_mov_b32_e32 v169, 0
	v_mov_b32_e32 v168, 0
	v_mov_b32_e32 v167, 0
	v_mov_b32_e32 v166, 0
	s_and_saveexec_b64 s[2:3], vcc
	s_cbranch_execz .LBB0_622
	s_movk_i32 s4, 0x100
	v_add_u32_e32 v167, -1, v186
	v_cmp_lt_u32_e32 vcc, s4, v186
	s_and_saveexec_b64 s[4:5], vcc
	s_xor_b64 s[4:5], exec, s[4:5]
	v_add_u32_e32 v166, 0xfffffeff, v186
	v_lshlrev_b32_e32 v167, 6, v167
	v_and_b32_e32 v167, 0x7c0, v167
	v_lshrrev_b32_e32 v166, 5, v166
	v_add3_u32 v166, v166, s9, v167
	s_andn2_saveexec_b64 s[4:5], s[4:5]
	v_add_u32_e32 v166, s10, v167
	s_or_b64 exec, exec, s[4:5]
	v_readlane_b32 s4, v254, 39
	v_readlane_b32 s5, v254, 40
	s_nop 1
	v_mov_b64_e32 v[168:169], s[4:5]
	s_movk_i32 s4, 0x6c00
	v_mad_i64_i32 v[166:167], s[4:5], v166, s4, v[168:169]
	v_lshl_add_u64 v[166:167], v[178:179], 1, v[166:167]
	v_add_co_u32_e32 v166, vcc, 0x1000, v166
	s_nop 1
	v_addc_co_u32_e32 v167, vcc, 0, v167, vcc
	global_load_dwordx4 v[166:169], v[166:167], off offset:1024
